# non-temporal (nt) hint on the norm1 x loads: single-use stream no longer allocates over dirty cache lines
# speedup vs baseline: 1.0090x; 1.0090x over previous
.LBB0_172:
	s_or_b64 exec, exec, s[0:1]
	s_add_i32 s0, 0, 0x23f00
	v_mov_b32_e32 v0, s0
	s_add_i32 s0, 0, 0x23f28
	v_mov_b32_e32 v2, s0
	s_add_i32 s0, 0, 0x23fa8
	s_mov_b32 s2, -1
	v_mov_b32_e32 v4, s0
	s_waitcnt lgkmcnt(0)
	s_barrier
	ds_read_b64 v[0:1], v0
	ds_read_b64 v[2:3], v2
	ds_read_b64 v[4:5], v4
	s_cmpk_lt_i32 s84, 0x4000
	s_cselect_b64 s[0:1], -1, 0
	s_waitcnt lgkmcnt(0)
	v_readfirstlane_b32 s24, v0
	v_readfirstlane_b32 s25, v1
	v_readfirstlane_b32 s4, v2
	v_readfirstlane_b32 s5, v3
	v_readfirstlane_b32 s3, v4
	s_cmpk_gt_i32 s84, 0x3fff
	v_readfirstlane_b32 s6, v5
	s_cbranch_scc1 .LBB0_177
	s_cmpk_lg_i32 s76, 0x100
	s_cbranch_scc1 .Lnorm1_generic
	s_ashr_i32 s85, s84, 31
	s_lshl_b64 s[10:11], s[84:85], 12
	s_add_u32 s10, s24, s10
	s_addc_u32 s11, s25, s11
	s_lshl_b64 s[12:13], s[84:85], 11
	s_add_u32 s12, s3, s12
	s_addc_u32 s13, s6, s13
	s_add_u32 s12, s12, 0x2800000
	s_addc_u32 s13, s13, 0
	s_add_u32 s14, s3, 0x1c00000
	s_addc_u32 s15, s6, 0
	s_add_u32 s16, s14, 0x1000
	s_addc_u32 s17, s15, 0
	v_mbcnt_lo_u32_b32 v176, -1, 0
	v_mbcnt_hi_u32_b32 v176, -1, v176
	v_lshlrev_b32_e32 v172, 4, v176
	v_lshlrev_b32_e32 v173, 3, v176
	v_xor_b32_e32 v174, 16, v176
	v_xor_b32_e32 v175, 32, v176
	v_lshlrev_b32_e32 v174, 2, v174
	v_lshlrev_b32_e32 v175, 2, v175
	v_and_b32_e32 v177, 1, v176
	v_cmp_eq_u32_e32 vcc, 1, v177
	v_mul_u32_u24_e32 v177, 0x1f8, v177
	v_add_u32_e32 v177, v177, v173
	global_load_dwordx4 v[0:3], v172, s[10:11] nt
	global_load_dwordx4 v[4:7], v172, s[10:11] offset:1024 nt
	global_load_dwordx4 v[8:11], v172, s[10:11] offset:2048 nt
	global_load_dwordx4 v[12:15], v172, s[10:11] offset:3072 nt
	s_add_u32 s10, s10, 0x800000
	s_addc_u32 s11, s11, 0
	global_load_dwordx4 v[16:19], v172, s[10:11] nt
	global_load_dwordx4 v[20:23], v172, s[10:11] offset:1024 nt
	global_load_dwordx4 v[24:27], v172, s[10:11] offset:2048 nt
	global_load_dwordx4 v[28:31], v172, s[10:11] offset:3072 nt
	s_add_u32 s10, s10, 0x800000
	s_addc_u32 s11, s11, 0
	global_load_dwordx4 v[64:67], v172, s[4:5]
	global_load_dwordx4 v[68:71], v172, s[4:5] offset:1024
	global_load_dwordx4 v[72:75], v172, s[4:5] offset:2048
	global_load_dwordx4 v[76:79], v172, s[4:5] offset:3072
	global_load_dwordx4 v[80:83], v172, s[16:17]
	global_load_dwordx4 v[84:87], v172, s[16:17] offset:1024
	global_load_dwordx4 v[88:91], v172, s[16:17] offset:2048
	global_load_dwordx4 v[92:95], v172, s[16:17] offset:3072
	global_load_dwordx4 v[112:115], v172, s[14:15]
	global_load_dwordx4 v[116:119], v172, s[14:15] offset:1024
	global_load_dwordx4 v[120:123], v172, s[14:15] offset:2048
	global_load_dwordx4 v[124:127], v172, s[14:15] offset:3072
	s_add_u32 s16, s16, 0x6000
	s_addc_u32 s17, s17, 0
	s_add_u32 s14, s14, 0x6000
	s_addc_u32 s15, s15, 0
	global_load_dwordx4 v[32:35], v172, s[10:11] nt
	global_load_dwordx4 v[36:39], v172, s[10:11] offset:1024 nt
	global_load_dwordx4 v[40:43], v172, s[10:11] offset:2048 nt
	global_load_dwordx4 v[44:47], v172, s[10:11] offset:3072 nt
	s_add_u32 s10, s10, 0x800000
	s_addc_u32 s11, s11, 0
	global_load_dwordx4 v[48:51], v172, s[10:11] nt
	global_load_dwordx4 v[52:55], v172, s[10:11] offset:1024 nt
	global_load_dwordx4 v[56:59], v172, s[10:11] offset:2048 nt
	global_load_dwordx4 v[60:63], v172, s[10:11] offset:3072 nt
	s_add_u32 s10, s10, 0x800000
	s_addc_u32 s11, s11, 0
	s_waitcnt vmcnt(24)
	v_mul_f32_e32 v156, v0, v0
	v_mul_f32_e32 v157, v4, v4
	v_mul_f32_e32 v158, v8, v8
	v_mul_f32_e32 v159, v12, v12
	v_fmac_f32_e32 v156, v1, v1
	v_fmac_f32_e32 v157, v5, v5
	v_fmac_f32_e32 v158, v9, v9
	v_fmac_f32_e32 v159, v13, v13
	v_fmac_f32_e32 v156, v2, v2
	v_fmac_f32_e32 v157, v6, v6
	v_fmac_f32_e32 v158, v10, v10
	v_fmac_f32_e32 v159, v14, v14
	v_fmac_f32_e32 v156, v3, v3
	v_fmac_f32_e32 v157, v7, v7
	v_fmac_f32_e32 v158, v11, v11
	v_fmac_f32_e32 v159, v15, v15
	v_add_f32_e32 v156, v156, v157
	v_add_f32_e32 v158, v158, v159
	v_add_f32_e32 v144, v156, v158
	global_load_dwordx4 v[96:99], v172, s[16:17]
	global_load_dwordx4 v[100:103], v172, s[16:17] offset:1024
	global_load_dwordx4 v[104:107], v172, s[16:17] offset:2048
	global_load_dwordx4 v[108:111], v172, s[16:17] offset:3072
	global_load_dwordx4 v[128:131], v172, s[14:15]
	global_load_dwordx4 v[132:135], v172, s[14:15] offset:1024
	global_load_dwordx4 v[136:139], v172, s[14:15] offset:2048
	global_load_dwordx4 v[140:143], v172, s[14:15] offset:3072
	s_add_u32 s16, s16, 0x6000
	s_addc_u32 s17, s17, 0
	s_add_u32 s14, s14, 0x6000
	s_addc_u32 s15, s15, 0
	s_nop 1
	v_add_f32_dpp v144, v144, v144 quad_perm:[1,0,3,2] row_mask:0xf bank_mask:0xf bound_ctrl:1
	s_nop 1
	v_add_f32_dpp v144, v144, v144 quad_perm:[2,3,0,1] row_mask:0xf bank_mask:0xf bound_ctrl:1
	s_nop 1
	v_add_f32_dpp v144, v144, v144 row_half_mirror row_mask:0xf bank_mask:0xf bound_ctrl:1
	s_nop 1
	v_add_f32_dpp v144, v144, v144 row_mirror row_mask:0xf bank_mask:0xf bound_ctrl:1
	s_nop 1
	ds_bpermute_b32 v145, v174, v144
	s_waitcnt lgkmcnt(0)
	v_add_f32_e32 v144, v144, v145
	ds_bpermute_b32 v145, v175, v144
	s_waitcnt lgkmcnt(0)
	v_add_f32_e32 v144, v144, v145
	v_mov_b32_e32 v145, 0x358637bd
	v_fmac_f32_e32 v145, 0x3a800000, v144
	v_rsq_f32_e32 v146, v145
	s_nop 0
	s_waitcnt vmcnt(24)
	s_waitcnt vmcnt(16)
	v_add_f32_e32 v80, 1.0, v80
	v_add_f32_e32 v81, 1.0, v81
	v_add_f32_e32 v82, 1.0, v82
	v_add_f32_e32 v83, 1.0, v83
	v_add_f32_e32 v84, 1.0, v84
	v_add_f32_e32 v85, 1.0, v85
	v_add_f32_e32 v86, 1.0, v86
	v_add_f32_e32 v87, 1.0, v87
	v_add_f32_e32 v88, 1.0, v88
	v_add_f32_e32 v89, 1.0, v89
	v_add_f32_e32 v90, 1.0, v90
	v_add_f32_e32 v91, 1.0, v91
	v_add_f32_e32 v92, 1.0, v92
	v_add_f32_e32 v93, 1.0, v93
	v_add_f32_e32 v94, 1.0, v94
	v_add_f32_e32 v95, 1.0, v95
	v_mul_f32_e32 v156, v0, v146
	v_mul_f32_e32 v157, v1, v146
	v_mul_f32_e32 v158, v2, v146
	v_mul_f32_e32 v159, v3, v146
	v_mul_f32_e32 v160, v4, v146
	v_mul_f32_e32 v161, v5, v146
	v_mul_f32_e32 v162, v6, v146
	v_mul_f32_e32 v163, v7, v146
	v_mul_f32_e32 v164, v8, v146
	v_mul_f32_e32 v165, v9, v146
	v_mul_f32_e32 v166, v10, v146
	v_mul_f32_e32 v167, v11, v146
	v_mul_f32_e32 v168, v12, v146
	v_mul_f32_e32 v169, v13, v146
	v_mul_f32_e32 v170, v14, v146
	v_mul_f32_e32 v171, v15, v146
	v_mul_f32_e32 v156, v64, v156
	v_mul_f32_e32 v157, v65, v157
	v_mul_f32_e32 v158, v66, v158
	v_mul_f32_e32 v159, v67, v159
	v_mul_f32_e32 v160, v68, v160
	v_mul_f32_e32 v161, v69, v161
	v_mul_f32_e32 v162, v70, v162
	v_mul_f32_e32 v163, v71, v163
	v_mul_f32_e32 v164, v72, v164
	v_mul_f32_e32 v165, v73, v165
	v_mul_f32_e32 v166, v74, v166
	v_mul_f32_e32 v167, v75, v167
	v_mul_f32_e32 v168, v76, v168
	v_mul_f32_e32 v169, v77, v169
	v_mul_f32_e32 v170, v78, v170
	v_mul_f32_e32 v171, v79, v171
	v_fma_f32 v156, v80, v156, v112
	v_fma_f32 v157, v81, v157, v113
	v_fma_f32 v158, v82, v158, v114
	v_fma_f32 v159, v83, v159, v115
	v_fma_f32 v160, v84, v160, v116
	v_fma_f32 v161, v85, v161, v117
	v_fma_f32 v162, v86, v162, v118
	v_fma_f32 v163, v87, v163, v119
	v_fma_f32 v164, v88, v164, v120
	v_fma_f32 v165, v89, v165, v121
	v_fma_f32 v166, v90, v166, v122
	v_fma_f32 v167, v91, v167, v123
	v_fma_f32 v168, v92, v168, v124
	v_fma_f32 v169, v93, v169, v125
	v_fma_f32 v170, v94, v170, v126
	v_fma_f32 v171, v95, v171, v127
	global_load_dwordx4 v[0:3], v172, s[10:11] nt
	global_load_dwordx4 v[4:7], v172, s[10:11] offset:1024 nt
	global_load_dwordx4 v[8:11], v172, s[10:11] offset:2048 nt
	global_load_dwordx4 v[12:15], v172, s[10:11] offset:3072 nt
	s_add_u32 s10, s10, 0x800000
	s_addc_u32 s11, s11, 0
	v_cvt_pk_bf16_f32 v148, v156, v157
	v_cvt_pk_bf16_f32 v149, v158, v159
	v_cvt_pk_bf16_f32 v150, v160, v161
	v_cvt_pk_bf16_f32 v151, v162, v163
	v_cvt_pk_bf16_f32 v152, v164, v165
	v_cvt_pk_bf16_f32 v153, v166, v167
	v_cvt_pk_bf16_f32 v154, v168, v169
	v_cvt_pk_bf16_f32 v155, v170, v171
	v_cndmask_b32_e32 v188, v150, v148, vcc
	v_cndmask_b32_e32 v189, v151, v149, vcc
	s_nop 1
	v_mov_b32_dpp v190, v188 quad_perm:[1,0,3,2] row_mask:0xf bank_mask:0xf
	v_mov_b32_dpp v191, v189 quad_perm:[1,0,3,2] row_mask:0xf bank_mask:0xf
	v_cndmask_b32_e32 v180, v148, v190, vcc
	v_cndmask_b32_e32 v181, v149, v191, vcc
	v_cndmask_b32_e32 v182, v190, v150, vcc
	v_cndmask_b32_e32 v183, v191, v151, vcc
	global_store_dwordx4 v177, v[180:183], s[12:13] sc1
	v_cndmask_b32_e32 v188, v154, v152, vcc
	v_cndmask_b32_e32 v189, v155, v153, vcc
	s_nop 1
	v_mov_b32_dpp v190, v188 quad_perm:[1,0,3,2] row_mask:0xf bank_mask:0xf
	v_mov_b32_dpp v191, v189 quad_perm:[1,0,3,2] row_mask:0xf bank_mask:0xf
	v_cndmask_b32_e32 v184, v152, v190, vcc
	v_cndmask_b32_e32 v185, v153, v191, vcc
	v_cndmask_b32_e32 v186, v190, v154, vcc
	v_cndmask_b32_e32 v187, v191, v155, vcc
	global_store_dwordx4 v177, v[184:187], s[12:13] offset:1024 sc1
	s_add_u32 s12, s12, 0x400000
	s_addc_u32 s13, s13, 0
	v_mul_f32_e32 v156, v16, v16
	v_mul_f32_e32 v157, v20, v20
	v_mul_f32_e32 v158, v24, v24
	v_mul_f32_e32 v159, v28, v28
	v_fmac_f32_e32 v156, v17, v17
	v_fmac_f32_e32 v157, v21, v21
	v_fmac_f32_e32 v158, v25, v25
	v_fmac_f32_e32 v159, v29, v29
	v_fmac_f32_e32 v156, v18, v18
	v_fmac_f32_e32 v157, v22, v22
	v_fmac_f32_e32 v158, v26, v26
	v_fmac_f32_e32 v159, v30, v30
	v_fmac_f32_e32 v156, v19, v19
	v_fmac_f32_e32 v157, v23, v23
	v_fmac_f32_e32 v158, v27, v27
	v_fmac_f32_e32 v159, v31, v31
	v_add_f32_e32 v156, v156, v157
	v_add_f32_e32 v158, v158, v159
	v_add_f32_e32 v144, v156, v158
	global_load_dwordx4 v[80:83], v172, s[16:17]
	global_load_dwordx4 v[84:87], v172, s[16:17] offset:1024
	global_load_dwordx4 v[88:91], v172, s[16:17] offset:2048
	global_load_dwordx4 v[92:95], v172, s[16:17] offset:3072
	global_load_dwordx4 v[112:115], v172, s[14:15]
	global_load_dwordx4 v[116:119], v172, s[14:15] offset:1024
	global_load_dwordx4 v[120:123], v172, s[14:15] offset:2048
	global_load_dwordx4 v[124:127], v172, s[14:15] offset:3072
	s_add_u32 s16, s16, 0x6000
	s_addc_u32 s17, s17, 0
	s_add_u32 s14, s14, 0x6000
	s_addc_u32 s15, s15, 0
	s_nop 1
	v_add_f32_dpp v144, v144, v144 quad_perm:[1,0,3,2] row_mask:0xf bank_mask:0xf bound_ctrl:1
	s_nop 1
	v_add_f32_dpp v144, v144, v144 quad_perm:[2,3,0,1] row_mask:0xf bank_mask:0xf bound_ctrl:1
	s_nop 1
	v_add_f32_dpp v144, v144, v144 row_half_mirror row_mask:0xf bank_mask:0xf bound_ctrl:1
	s_nop 1
	v_add_f32_dpp v144, v144, v144 row_mirror row_mask:0xf bank_mask:0xf bound_ctrl:1
	s_nop 1
	ds_bpermute_b32 v145, v174, v144
	s_waitcnt lgkmcnt(0)
	v_add_f32_e32 v144, v144, v145
	ds_bpermute_b32 v145, v175, v144
	s_waitcnt lgkmcnt(0)
	v_add_f32_e32 v144, v144, v145
	v_mov_b32_e32 v145, 0x358637bd
	v_fmac_f32_e32 v145, 0x3a800000, v144
	v_rsq_f32_e32 v146, v145
	s_nop 0
	s_waitcnt vmcnt(14)
	v_add_f32_e32 v96, 1.0, v96
	v_add_f32_e32 v97, 1.0, v97
	v_add_f32_e32 v98, 1.0, v98
	v_add_f32_e32 v99, 1.0, v99
	v_add_f32_e32 v100, 1.0, v100
	v_add_f32_e32 v101, 1.0, v101
	v_add_f32_e32 v102, 1.0, v102
	v_add_f32_e32 v103, 1.0, v103
	v_add_f32_e32 v104, 1.0, v104
	v_add_f32_e32 v105, 1.0, v105
	v_add_f32_e32 v106, 1.0, v106
	v_add_f32_e32 v107, 1.0, v107
	v_add_f32_e32 v108, 1.0, v108
	v_add_f32_e32 v109, 1.0, v109
	v_add_f32_e32 v110, 1.0, v110
	v_add_f32_e32 v111, 1.0, v111
	v_mul_f32_e32 v156, v16, v146
	v_mul_f32_e32 v157, v17, v146
	v_mul_f32_e32 v158, v18, v146
	v_mul_f32_e32 v159, v19, v146
	v_mul_f32_e32 v160, v20, v146
	v_mul_f32_e32 v161, v21, v146
	v_mul_f32_e32 v162, v22, v146
	v_mul_f32_e32 v163, v23, v146
	v_mul_f32_e32 v164, v24, v146
	v_mul_f32_e32 v165, v25, v146
	v_mul_f32_e32 v166, v26, v146
	v_mul_f32_e32 v167, v27, v146
	v_mul_f32_e32 v168, v28, v146
	v_mul_f32_e32 v169, v29, v146
	v_mul_f32_e32 v170, v30, v146
	v_mul_f32_e32 v171, v31, v146
	v_mul_f32_e32 v156, v64, v156
	v_mul_f32_e32 v157, v65, v157
	v_mul_f32_e32 v158, v66, v158
	v_mul_f32_e32 v159, v67, v159
	v_mul_f32_e32 v160, v68, v160
	v_mul_f32_e32 v161, v69, v161
	v_mul_f32_e32 v162, v70, v162
	v_mul_f32_e32 v163, v71, v163
	v_mul_f32_e32 v164, v72, v164
	v_mul_f32_e32 v165, v73, v165
	v_mul_f32_e32 v166, v74, v166
	v_mul_f32_e32 v167, v75, v167
	v_mul_f32_e32 v168, v76, v168
	v_mul_f32_e32 v169, v77, v169
	v_mul_f32_e32 v170, v78, v170
	v_mul_f32_e32 v171, v79, v171
	v_fma_f32 v156, v96, v156, v128
	v_fma_f32 v157, v97, v157, v129
	v_fma_f32 v158, v98, v158, v130
	v_fma_f32 v159, v99, v159, v131
	v_fma_f32 v160, v100, v160, v132
	v_fma_f32 v161, v101, v161, v133
	v_fma_f32 v162, v102, v162, v134
	v_fma_f32 v163, v103, v163, v135
	v_fma_f32 v164, v104, v164, v136
	v_fma_f32 v165, v105, v165, v137
	v_fma_f32 v166, v106, v166, v138
	v_fma_f32 v167, v107, v167, v139
	v_fma_f32 v168, v108, v168, v140
	v_fma_f32 v169, v109, v169, v141
	v_fma_f32 v170, v110, v170, v142
	v_fma_f32 v171, v111, v171, v143
	global_load_dwordx4 v[16:19], v172, s[10:11] nt
	global_load_dwordx4 v[20:23], v172, s[10:11] offset:1024 nt
	global_load_dwordx4 v[24:27], v172, s[10:11] offset:2048 nt
	global_load_dwordx4 v[28:31], v172, s[10:11] offset:3072 nt
	s_add_u32 s10, s10, 0x800000
	s_addc_u32 s11, s11, 0
	v_cvt_pk_bf16_f32 v148, v156, v157
	v_cvt_pk_bf16_f32 v149, v158, v159
	v_cvt_pk_bf16_f32 v150, v160, v161
	v_cvt_pk_bf16_f32 v151, v162, v163
	v_cvt_pk_bf16_f32 v152, v164, v165
	v_cvt_pk_bf16_f32 v153, v166, v167
	v_cvt_pk_bf16_f32 v154, v168, v169
	v_cvt_pk_bf16_f32 v155, v170, v171
	v_cndmask_b32_e32 v188, v150, v148, vcc
	v_cndmask_b32_e32 v189, v151, v149, vcc
	s_nop 1
	v_mov_b32_dpp v190, v188 quad_perm:[1,0,3,2] row_mask:0xf bank_mask:0xf
	v_mov_b32_dpp v191, v189 quad_perm:[1,0,3,2] row_mask:0xf bank_mask:0xf
	v_cndmask_b32_e32 v180, v148, v190, vcc
	v_cndmask_b32_e32 v181, v149, v191, vcc
	v_cndmask_b32_e32 v182, v190, v150, vcc
	v_cndmask_b32_e32 v183, v191, v151, vcc
	global_store_dwordx4 v177, v[180:183], s[12:13] sc1
	v_cndmask_b32_e32 v188, v154, v152, vcc
	v_cndmask_b32_e32 v189, v155, v153, vcc
	s_nop 1
	v_mov_b32_dpp v190, v188 quad_perm:[1,0,3,2] row_mask:0xf bank_mask:0xf
	v_mov_b32_dpp v191, v189 quad_perm:[1,0,3,2] row_mask:0xf bank_mask:0xf
	v_cndmask_b32_e32 v184, v152, v190, vcc
	v_cndmask_b32_e32 v185, v153, v191, vcc
	v_cndmask_b32_e32 v186, v190, v154, vcc
	v_cndmask_b32_e32 v187, v191, v155, vcc
	global_store_dwordx4 v177, v[184:187], s[12:13] offset:1024 sc1
	s_add_u32 s12, s12, 0x400000
	s_addc_u32 s13, s13, 0
	v_mul_f32_e32 v156, v32, v32
	v_mul_f32_e32 v157, v36, v36
	v_mul_f32_e32 v158, v40, v40
	v_mul_f32_e32 v159, v44, v44
	v_fmac_f32_e32 v156, v33, v33
	v_fmac_f32_e32 v157, v37, v37
	v_fmac_f32_e32 v158, v41, v41
	v_fmac_f32_e32 v159, v45, v45
	v_fmac_f32_e32 v156, v34, v34
	v_fmac_f32_e32 v157, v38, v38
	v_fmac_f32_e32 v158, v42, v42
	v_fmac_f32_e32 v159, v46, v46
	v_fmac_f32_e32 v156, v35, v35
	v_fmac_f32_e32 v157, v39, v39
	v_fmac_f32_e32 v158, v43, v43
	v_fmac_f32_e32 v159, v47, v47
	v_add_f32_e32 v156, v156, v157
	v_add_f32_e32 v158, v158, v159
	v_add_f32_e32 v144, v156, v158
	global_load_dwordx4 v[96:99], v172, s[16:17]
	global_load_dwordx4 v[100:103], v172, s[16:17] offset:1024
	global_load_dwordx4 v[104:107], v172, s[16:17] offset:2048
	global_load_dwordx4 v[108:111], v172, s[16:17] offset:3072
	global_load_dwordx4 v[128:131], v172, s[14:15]
	global_load_dwordx4 v[132:135], v172, s[14:15] offset:1024
	global_load_dwordx4 v[136:139], v172, s[14:15] offset:2048
	global_load_dwordx4 v[140:143], v172, s[14:15] offset:3072
	s_add_u32 s16, s16, 0x6000
	s_addc_u32 s17, s17, 0
	s_add_u32 s14, s14, 0x6000
	s_addc_u32 s15, s15, 0
	s_nop 1
	v_add_f32_dpp v144, v144, v144 quad_perm:[1,0,3,2] row_mask:0xf bank_mask:0xf bound_ctrl:1
	s_nop 1
	v_add_f32_dpp v144, v144, v144 quad_perm:[2,3,0,1] row_mask:0xf bank_mask:0xf bound_ctrl:1
	s_nop 1
	v_add_f32_dpp v144, v144, v144 row_half_mirror row_mask:0xf bank_mask:0xf bound_ctrl:1
	s_nop 1
	v_add_f32_dpp v144, v144, v144 row_mirror row_mask:0xf bank_mask:0xf bound_ctrl:1
	s_nop 1
	ds_bpermute_b32 v145, v174, v144
	s_waitcnt lgkmcnt(0)
	v_add_f32_e32 v144, v144, v145
	ds_bpermute_b32 v145, v175, v144
	s_waitcnt lgkmcnt(0)
	v_add_f32_e32 v144, v144, v145
	v_mov_b32_e32 v145, 0x358637bd
	v_fmac_f32_e32 v145, 0x3a800000, v144
	v_rsq_f32_e32 v146, v145
	s_nop 0
	s_waitcnt vmcnt(14)
	v_add_f32_e32 v80, 1.0, v80
	v_add_f32_e32 v81, 1.0, v81
	v_add_f32_e32 v82, 1.0, v82
	v_add_f32_e32 v83, 1.0, v83
	v_add_f32_e32 v84, 1.0, v84
	v_add_f32_e32 v85, 1.0, v85
	v_add_f32_e32 v86, 1.0, v86
	v_add_f32_e32 v87, 1.0, v87
	v_add_f32_e32 v88, 1.0, v88
	v_add_f32_e32 v89, 1.0, v89
	v_add_f32_e32 v90, 1.0, v90
	v_add_f32_e32 v91, 1.0, v91
	v_add_f32_e32 v92, 1.0, v92
	v_add_f32_e32 v93, 1.0, v93
	v_add_f32_e32 v94, 1.0, v94
	v_add_f32_e32 v95, 1.0, v95
	v_mul_f32_e32 v156, v32, v146
	v_mul_f32_e32 v157, v33, v146
	v_mul_f32_e32 v158, v34, v146
	v_mul_f32_e32 v159, v35, v146
	v_mul_f32_e32 v160, v36, v146
	v_mul_f32_e32 v161, v37, v146
	v_mul_f32_e32 v162, v38, v146
	v_mul_f32_e32 v163, v39, v146
	v_mul_f32_e32 v164, v40, v146
	v_mul_f32_e32 v165, v41, v146
	v_mul_f32_e32 v166, v42, v146
	v_mul_f32_e32 v167, v43, v146
	v_mul_f32_e32 v168, v44, v146
	v_mul_f32_e32 v169, v45, v146
	v_mul_f32_e32 v170, v46, v146
	v_mul_f32_e32 v171, v47, v146
	v_mul_f32_e32 v156, v64, v156
	v_mul_f32_e32 v157, v65, v157
	v_mul_f32_e32 v158, v66, v158
	v_mul_f32_e32 v159, v67, v159
	v_mul_f32_e32 v160, v68, v160
	v_mul_f32_e32 v161, v69, v161
	v_mul_f32_e32 v162, v70, v162
	v_mul_f32_e32 v163, v71, v163
	v_mul_f32_e32 v164, v72, v164
	v_mul_f32_e32 v165, v73, v165
	v_mul_f32_e32 v166, v74, v166
	v_mul_f32_e32 v167, v75, v167
	v_mul_f32_e32 v168, v76, v168
	v_mul_f32_e32 v169, v77, v169
	v_mul_f32_e32 v170, v78, v170
	v_mul_f32_e32 v171, v79, v171
	v_fma_f32 v156, v80, v156, v112
	v_fma_f32 v157, v81, v157, v113
	v_fma_f32 v158, v82, v158, v114
	v_fma_f32 v159, v83, v159, v115
	v_fma_f32 v160, v84, v160, v116
	v_fma_f32 v161, v85, v161, v117
	v_fma_f32 v162, v86, v162, v118
	v_fma_f32 v163, v87, v163, v119
	v_fma_f32 v164, v88, v164, v120
	v_fma_f32 v165, v89, v165, v121
	v_fma_f32 v166, v90, v166, v122
	v_fma_f32 v167, v91, v167, v123
	v_fma_f32 v168, v92, v168, v124
	v_fma_f32 v169, v93, v169, v125
	v_fma_f32 v170, v94, v170, v126
	v_fma_f32 v171, v95, v171, v127
	global_load_dwordx4 v[32:35], v172, s[10:11] nt
	global_load_dwordx4 v[36:39], v172, s[10:11] offset:1024 nt
	global_load_dwordx4 v[40:43], v172, s[10:11] offset:2048 nt
	global_load_dwordx4 v[44:47], v172, s[10:11] offset:3072 nt
	s_add_u32 s10, s10, 0x800000
	s_addc_u32 s11, s11, 0
	v_cvt_pk_bf16_f32 v148, v156, v157
	v_cvt_pk_bf16_f32 v149, v158, v159
	v_cvt_pk_bf16_f32 v150, v160, v161
	v_cvt_pk_bf16_f32 v151, v162, v163
	v_cvt_pk_bf16_f32 v152, v164, v165
	v_cvt_pk_bf16_f32 v153, v166, v167
	v_cvt_pk_bf16_f32 v154, v168, v169
	v_cvt_pk_bf16_f32 v155, v170, v171
	v_cndmask_b32_e32 v188, v150, v148, vcc
	v_cndmask_b32_e32 v189, v151, v149, vcc
	s_nop 1
	v_mov_b32_dpp v190, v188 quad_perm:[1,0,3,2] row_mask:0xf bank_mask:0xf
	v_mov_b32_dpp v191, v189 quad_perm:[1,0,3,2] row_mask:0xf bank_mask:0xf
	v_cndmask_b32_e32 v180, v148, v190, vcc
	v_cndmask_b32_e32 v181, v149, v191, vcc
	v_cndmask_b32_e32 v182, v190, v150, vcc
	v_cndmask_b32_e32 v183, v191, v151, vcc
	global_store_dwordx4 v177, v[180:183], s[12:13] sc1
	v_cndmask_b32_e32 v188, v154, v152, vcc
	v_cndmask_b32_e32 v189, v155, v153, vcc
	s_nop 1
	v_mov_b32_dpp v190, v188 quad_perm:[1,0,3,2] row_mask:0xf bank_mask:0xf
	v_mov_b32_dpp v191, v189 quad_perm:[1,0,3,2] row_mask:0xf bank_mask:0xf
	v_cndmask_b32_e32 v184, v152, v190, vcc
	v_cndmask_b32_e32 v185, v153, v191, vcc
	v_cndmask_b32_e32 v186, v190, v154, vcc
	v_cndmask_b32_e32 v187, v191, v155, vcc
	global_store_dwordx4 v177, v[184:187], s[12:13] offset:1024 sc1
	s_add_u32 s12, s12, 0x400000
	s_addc_u32 s13, s13, 0
	v_mul_f32_e32 v156, v48, v48
	v_mul_f32_e32 v157, v52, v52
	v_mul_f32_e32 v158, v56, v56
	v_mul_f32_e32 v159, v60, v60
	v_fmac_f32_e32 v156, v49, v49
	v_fmac_f32_e32 v157, v53, v53
	v_fmac_f32_e32 v158, v57, v57
	v_fmac_f32_e32 v159, v61, v61
	v_fmac_f32_e32 v156, v50, v50
	v_fmac_f32_e32 v157, v54, v54
	v_fmac_f32_e32 v158, v58, v58
	v_fmac_f32_e32 v159, v62, v62
	v_fmac_f32_e32 v156, v51, v51
	v_fmac_f32_e32 v157, v55, v55
	v_fmac_f32_e32 v158, v59, v59
	v_fmac_f32_e32 v159, v63, v63
	v_add_f32_e32 v156, v156, v157
	v_add_f32_e32 v158, v158, v159
	v_add_f32_e32 v144, v156, v158
	global_load_dwordx4 v[80:83], v172, s[16:17]
	global_load_dwordx4 v[84:87], v172, s[16:17] offset:1024
	global_load_dwordx4 v[88:91], v172, s[16:17] offset:2048
	global_load_dwordx4 v[92:95], v172, s[16:17] offset:3072
	global_load_dwordx4 v[112:115], v172, s[14:15]
	global_load_dwordx4 v[116:119], v172, s[14:15] offset:1024
	global_load_dwordx4 v[120:123], v172, s[14:15] offset:2048
	global_load_dwordx4 v[124:127], v172, s[14:15] offset:3072
	s_add_u32 s16, s16, 0x6000
	s_addc_u32 s17, s17, 0
	s_add_u32 s14, s14, 0x6000
	s_addc_u32 s15, s15, 0
	s_nop 1
	v_add_f32_dpp v144, v144, v144 quad_perm:[1,0,3,2] row_mask:0xf bank_mask:0xf bound_ctrl:1
	s_nop 1
	v_add_f32_dpp v144, v144, v144 quad_perm:[2,3,0,1] row_mask:0xf bank_mask:0xf bound_ctrl:1
	s_nop 1
	v_add_f32_dpp v144, v144, v144 row_half_mirror row_mask:0xf bank_mask:0xf bound_ctrl:1
	s_nop 1
	v_add_f32_dpp v144, v144, v144 row_mirror row_mask:0xf bank_mask:0xf bound_ctrl:1
	s_nop 1
	ds_bpermute_b32 v145, v174, v144
	s_waitcnt lgkmcnt(0)
	v_add_f32_e32 v144, v144, v145
	ds_bpermute_b32 v145, v175, v144
	s_waitcnt lgkmcnt(0)
	v_add_f32_e32 v144, v144, v145
	v_mov_b32_e32 v145, 0x358637bd
	v_fmac_f32_e32 v145, 0x3a800000, v144
	v_rsq_f32_e32 v146, v145
	s_nop 0
	s_waitcnt vmcnt(14)
	v_add_f32_e32 v96, 1.0, v96
	v_add_f32_e32 v97, 1.0, v97
	v_add_f32_e32 v98, 1.0, v98
	v_add_f32_e32 v99, 1.0, v99
	v_add_f32_e32 v100, 1.0, v100
	v_add_f32_e32 v101, 1.0, v101
	v_add_f32_e32 v102, 1.0, v102
	v_add_f32_e32 v103, 1.0, v103
	v_add_f32_e32 v104, 1.0, v104
	v_add_f32_e32 v105, 1.0, v105
	v_add_f32_e32 v106, 1.0, v106
	v_add_f32_e32 v107, 1.0, v107
	v_add_f32_e32 v108, 1.0, v108
	v_add_f32_e32 v109, 1.0, v109
	v_add_f32_e32 v110, 1.0, v110
	v_add_f32_e32 v111, 1.0, v111
	v_mul_f32_e32 v156, v48, v146
	v_mul_f32_e32 v157, v49, v146
	v_mul_f32_e32 v158, v50, v146
	v_mul_f32_e32 v159, v51, v146
	v_mul_f32_e32 v160, v52, v146
	v_mul_f32_e32 v161, v53, v146
	v_mul_f32_e32 v162, v54, v146
	v_mul_f32_e32 v163, v55, v146
	v_mul_f32_e32 v164, v56, v146
	v_mul_f32_e32 v165, v57, v146
	v_mul_f32_e32 v166, v58, v146
	v_mul_f32_e32 v167, v59, v146
	v_mul_f32_e32 v168, v60, v146
	v_mul_f32_e32 v169, v61, v146
	v_mul_f32_e32 v170, v62, v146
	v_mul_f32_e32 v171, v63, v146
	v_mul_f32_e32 v156, v64, v156
	v_mul_f32_e32 v157, v65, v157
	v_mul_f32_e32 v158, v66, v158
	v_mul_f32_e32 v159, v67, v159
	v_mul_f32_e32 v160, v68, v160
	v_mul_f32_e32 v161, v69, v161
	v_mul_f32_e32 v162, v70, v162
	v_mul_f32_e32 v163, v71, v163
	v_mul_f32_e32 v164, v72, v164
	v_mul_f32_e32 v165, v73, v165
	v_mul_f32_e32 v166, v74, v166
	v_mul_f32_e32 v167, v75, v167
	v_mul_f32_e32 v168, v76, v168
	v_mul_f32_e32 v169, v77, v169
	v_mul_f32_e32 v170, v78, v170
	v_mul_f32_e32 v171, v79, v171
	v_fma_f32 v156, v96, v156, v128
	v_fma_f32 v157, v97, v157, v129
	v_fma_f32 v158, v98, v158, v130
	v_fma_f32 v159, v99, v159, v131
	v_fma_f32 v160, v100, v160, v132
	v_fma_f32 v161, v101, v161, v133
	v_fma_f32 v162, v102, v162, v134
	v_fma_f32 v163, v103, v163, v135
	v_fma_f32 v164, v104, v164, v136
	v_fma_f32 v165, v105, v165, v137
	v_fma_f32 v166, v106, v166, v138
	v_fma_f32 v167, v107, v167, v139
	v_fma_f32 v168, v108, v168, v140
	v_fma_f32 v169, v109, v169, v141
	v_fma_f32 v170, v110, v170, v142
	v_fma_f32 v171, v111, v171, v143
	global_load_dwordx4 v[48:51], v172, s[10:11] nt
	global_load_dwordx4 v[52:55], v172, s[10:11] offset:1024 nt
	global_load_dwordx4 v[56:59], v172, s[10:11] offset:2048 nt
	global_load_dwordx4 v[60:63], v172, s[10:11] offset:3072 nt
	s_add_u32 s10, s10, 0x800000
	s_addc_u32 s11, s11, 0
	v_cvt_pk_bf16_f32 v148, v156, v157
	v_cvt_pk_bf16_f32 v149, v158, v159
	v_cvt_pk_bf16_f32 v150, v160, v161
	v_cvt_pk_bf16_f32 v151, v162, v163
	v_cvt_pk_bf16_f32 v152, v164, v165
	v_cvt_pk_bf16_f32 v153, v166, v167
	v_cvt_pk_bf16_f32 v154, v168, v169
	v_cvt_pk_bf16_f32 v155, v170, v171
	v_cndmask_b32_e32 v188, v150, v148, vcc
	v_cndmask_b32_e32 v189, v151, v149, vcc
	s_nop 1
	v_mov_b32_dpp v190, v188 quad_perm:[1,0,3,2] row_mask:0xf bank_mask:0xf
	v_mov_b32_dpp v191, v189 quad_perm:[1,0,3,2] row_mask:0xf bank_mask:0xf
	v_cndmask_b32_e32 v180, v148, v190, vcc
	v_cndmask_b32_e32 v181, v149, v191, vcc
	v_cndmask_b32_e32 v182, v190, v150, vcc
	v_cndmask_b32_e32 v183, v191, v151, vcc
	global_store_dwordx4 v177, v[180:183], s[12:13] sc1
	v_cndmask_b32_e32 v188, v154, v152, vcc
	v_cndmask_b32_e32 v189, v155, v153, vcc
	s_nop 1
	v_mov_b32_dpp v190, v188 quad_perm:[1,0,3,2] row_mask:0xf bank_mask:0xf
	v_mov_b32_dpp v191, v189 quad_perm:[1,0,3,2] row_mask:0xf bank_mask:0xf
	v_cndmask_b32_e32 v184, v152, v190, vcc
	v_cndmask_b32_e32 v185, v153, v191, vcc
	v_cndmask_b32_e32 v186, v190, v154, vcc
	v_cndmask_b32_e32 v187, v191, v155, vcc
	global_store_dwordx4 v177, v[184:187], s[12:13] offset:1024 sc1
	s_add_u32 s12, s12, 0x400000
	s_addc_u32 s13, s13, 0
	v_mul_f32_e32 v156, v0, v0
	v_mul_f32_e32 v157, v4, v4
	v_mul_f32_e32 v158, v8, v8
	v_mul_f32_e32 v159, v12, v12
	v_fmac_f32_e32 v156, v1, v1
	v_fmac_f32_e32 v157, v5, v5
	v_fmac_f32_e32 v158, v9, v9
	v_fmac_f32_e32 v159, v13, v13
	v_fmac_f32_e32 v156, v2, v2
	v_fmac_f32_e32 v157, v6, v6
	v_fmac_f32_e32 v158, v10, v10
	v_fmac_f32_e32 v159, v14, v14
	v_fmac_f32_e32 v156, v3, v3
	v_fmac_f32_e32 v157, v7, v7
	v_fmac_f32_e32 v158, v11, v11
	v_fmac_f32_e32 v159, v15, v15
	v_add_f32_e32 v156, v156, v157
	v_add_f32_e32 v158, v158, v159
	v_add_f32_e32 v144, v156, v158
	global_load_dwordx4 v[96:99], v172, s[16:17]
	global_load_dwordx4 v[100:103], v172, s[16:17] offset:1024
	global_load_dwordx4 v[104:107], v172, s[16:17] offset:2048
	global_load_dwordx4 v[108:111], v172, s[16:17] offset:3072
	global_load_dwordx4 v[128:131], v172, s[14:15]
	global_load_dwordx4 v[132:135], v172, s[14:15] offset:1024
	global_load_dwordx4 v[136:139], v172, s[14:15] offset:2048
	global_load_dwordx4 v[140:143], v172, s[14:15] offset:3072
	s_add_u32 s16, s16, 0x6000
	s_addc_u32 s17, s17, 0
	s_add_u32 s14, s14, 0x6000
	s_addc_u32 s15, s15, 0
	s_nop 1
	v_add_f32_dpp v144, v144, v144 quad_perm:[1,0,3,2] row_mask:0xf bank_mask:0xf bound_ctrl:1
	s_nop 1
	v_add_f32_dpp v144, v144, v144 quad_perm:[2,3,0,1] row_mask:0xf bank_mask:0xf bound_ctrl:1
	s_nop 1
	v_add_f32_dpp v144, v144, v144 row_half_mirror row_mask:0xf bank_mask:0xf bound_ctrl:1
	s_nop 1
	v_add_f32_dpp v144, v144, v144 row_mirror row_mask:0xf bank_mask:0xf bound_ctrl:1
	s_nop 1
	ds_bpermute_b32 v145, v174, v144
	s_waitcnt lgkmcnt(0)
	v_add_f32_e32 v144, v144, v145
	ds_bpermute_b32 v145, v175, v144
	s_waitcnt lgkmcnt(0)
	v_add_f32_e32 v144, v144, v145
	v_mov_b32_e32 v145, 0x358637bd
	v_fmac_f32_e32 v145, 0x3a800000, v144
	v_rsq_f32_e32 v146, v145
	s_nop 0
	s_waitcnt vmcnt(14)
	v_add_f32_e32 v80, 1.0, v80
	v_add_f32_e32 v81, 1.0, v81
	v_add_f32_e32 v82, 1.0, v82
	v_add_f32_e32 v83, 1.0, v83
	v_add_f32_e32 v84, 1.0, v84
	v_add_f32_e32 v85, 1.0, v85
	v_add_f32_e32 v86, 1.0, v86
	v_add_f32_e32 v87, 1.0, v87
	v_add_f32_e32 v88, 1.0, v88
	v_add_f32_e32 v89, 1.0, v89
	v_add_f32_e32 v90, 1.0, v90
	v_add_f32_e32 v91, 1.0, v91
	v_add_f32_e32 v92, 1.0, v92
	v_add_f32_e32 v93, 1.0, v93
	v_add_f32_e32 v94, 1.0, v94
	v_add_f32_e32 v95, 1.0, v95
	v_mul_f32_e32 v156, v0, v146
	v_mul_f32_e32 v157, v1, v146
	v_mul_f32_e32 v158, v2, v146
	v_mul_f32_e32 v159, v3, v146
	v_mul_f32_e32 v160, v4, v146
	v_mul_f32_e32 v161, v5, v146
	v_mul_f32_e32 v162, v6, v146
	v_mul_f32_e32 v163, v7, v146
	v_mul_f32_e32 v164, v8, v146
	v_mul_f32_e32 v165, v9, v146
	v_mul_f32_e32 v166, v10, v146
	v_mul_f32_e32 v167, v11, v146
	v_mul_f32_e32 v168, v12, v146
	v_mul_f32_e32 v169, v13, v146
	v_mul_f32_e32 v170, v14, v146
	v_mul_f32_e32 v171, v15, v146
	v_mul_f32_e32 v156, v64, v156
	v_mul_f32_e32 v157, v65, v157
	v_mul_f32_e32 v158, v66, v158
	v_mul_f32_e32 v159, v67, v159
	v_mul_f32_e32 v160, v68, v160
	v_mul_f32_e32 v161, v69, v161
	v_mul_f32_e32 v162, v70, v162
	v_mul_f32_e32 v163, v71, v163
	v_mul_f32_e32 v164, v72, v164
	v_mul_f32_e32 v165, v73, v165
	v_mul_f32_e32 v166, v74, v166
	v_mul_f32_e32 v167, v75, v167
	v_mul_f32_e32 v168, v76, v168
	v_mul_f32_e32 v169, v77, v169
	v_mul_f32_e32 v170, v78, v170
	v_mul_f32_e32 v171, v79, v171
	v_fma_f32 v156, v80, v156, v112
	v_fma_f32 v157, v81, v157, v113
	v_fma_f32 v158, v82, v158, v114
	v_fma_f32 v159, v83, v159, v115
	v_fma_f32 v160, v84, v160, v116
	v_fma_f32 v161, v85, v161, v117
	v_fma_f32 v162, v86, v162, v118
	v_fma_f32 v163, v87, v163, v119
	v_fma_f32 v164, v88, v164, v120
	v_fma_f32 v165, v89, v165, v121
	v_fma_f32 v166, v90, v166, v122
	v_fma_f32 v167, v91, v167, v123
	v_fma_f32 v168, v92, v168, v124
	v_fma_f32 v169, v93, v169, v125
	v_fma_f32 v170, v94, v170, v126
	v_fma_f32 v171, v95, v171, v127
	v_cvt_pk_bf16_f32 v148, v156, v157
	v_cvt_pk_bf16_f32 v149, v158, v159
	v_cvt_pk_bf16_f32 v150, v160, v161
	v_cvt_pk_bf16_f32 v151, v162, v163
	v_cvt_pk_bf16_f32 v152, v164, v165
	v_cvt_pk_bf16_f32 v153, v166, v167
	v_cvt_pk_bf16_f32 v154, v168, v169
	v_cvt_pk_bf16_f32 v155, v170, v171
	v_cndmask_b32_e32 v188, v150, v148, vcc
	v_cndmask_b32_e32 v189, v151, v149, vcc
	s_nop 1
	v_mov_b32_dpp v190, v188 quad_perm:[1,0,3,2] row_mask:0xf bank_mask:0xf
	v_mov_b32_dpp v191, v189 quad_perm:[1,0,3,2] row_mask:0xf bank_mask:0xf
	v_cndmask_b32_e32 v180, v148, v190, vcc
	v_cndmask_b32_e32 v181, v149, v191, vcc
	v_cndmask_b32_e32 v182, v190, v150, vcc
	v_cndmask_b32_e32 v183, v191, v151, vcc
	global_store_dwordx4 v177, v[180:183], s[12:13] sc1
	v_cndmask_b32_e32 v188, v154, v152, vcc
	v_cndmask_b32_e32 v189, v155, v153, vcc
	s_nop 1
	v_mov_b32_dpp v190, v188 quad_perm:[1,0,3,2] row_mask:0xf bank_mask:0xf
	v_mov_b32_dpp v191, v189 quad_perm:[1,0,3,2] row_mask:0xf bank_mask:0xf
	v_cndmask_b32_e32 v184, v152, v190, vcc
	v_cndmask_b32_e32 v185, v153, v191, vcc
	v_cndmask_b32_e32 v186, v190, v154, vcc
	v_cndmask_b32_e32 v187, v191, v155, vcc
	global_store_dwordx4 v177, v[184:187], s[12:13] offset:1024 sc1
	s_add_u32 s12, s12, 0x400000
	s_addc_u32 s13, s13, 0
	v_mul_f32_e32 v156, v16, v16
	v_mul_f32_e32 v157, v20, v20
	v_mul_f32_e32 v158, v24, v24
	v_mul_f32_e32 v159, v28, v28
	v_fmac_f32_e32 v156, v17, v17
	v_fmac_f32_e32 v157, v21, v21
	v_fmac_f32_e32 v158, v25, v25
	v_fmac_f32_e32 v159, v29, v29
	v_fmac_f32_e32 v156, v18, v18
	v_fmac_f32_e32 v157, v22, v22
	v_fmac_f32_e32 v158, v26, v26
	v_fmac_f32_e32 v159, v30, v30
	v_fmac_f32_e32 v156, v19, v19
	v_fmac_f32_e32 v157, v23, v23
	v_fmac_f32_e32 v158, v27, v27
	v_fmac_f32_e32 v159, v31, v31
	v_add_f32_e32 v156, v156, v157
	v_add_f32_e32 v158, v158, v159
	v_add_f32_e32 v144, v156, v158
	global_load_dwordx4 v[80:83], v172, s[16:17]
	global_load_dwordx4 v[84:87], v172, s[16:17] offset:1024
	global_load_dwordx4 v[88:91], v172, s[16:17] offset:2048
	global_load_dwordx4 v[92:95], v172, s[16:17] offset:3072
	global_load_dwordx4 v[112:115], v172, s[14:15]
	global_load_dwordx4 v[116:119], v172, s[14:15] offset:1024
	global_load_dwordx4 v[120:123], v172, s[14:15] offset:2048
	global_load_dwordx4 v[124:127], v172, s[14:15] offset:3072
	s_add_u32 s16, s16, 0x6000
	s_addc_u32 s17, s17, 0
	s_add_u32 s14, s14, 0x6000
	s_addc_u32 s15, s15, 0
	s_nop 1
	v_add_f32_dpp v144, v144, v144 quad_perm:[1,0,3,2] row_mask:0xf bank_mask:0xf bound_ctrl:1
	s_nop 1
	v_add_f32_dpp v144, v144, v144 quad_perm:[2,3,0,1] row_mask:0xf bank_mask:0xf bound_ctrl:1
	s_nop 1
	v_add_f32_dpp v144, v144, v144 row_half_mirror row_mask:0xf bank_mask:0xf bound_ctrl:1
	s_nop 1
	v_add_f32_dpp v144, v144, v144 row_mirror row_mask:0xf bank_mask:0xf bound_ctrl:1
	s_nop 1
	ds_bpermute_b32 v145, v174, v144
	s_waitcnt lgkmcnt(0)
	v_add_f32_e32 v144, v144, v145
	ds_bpermute_b32 v145, v175, v144
	s_waitcnt lgkmcnt(0)
	v_add_f32_e32 v144, v144, v145
	v_mov_b32_e32 v145, 0x358637bd
	v_fmac_f32_e32 v145, 0x3a800000, v144
	v_rsq_f32_e32 v146, v145
	s_nop 0
	s_waitcnt vmcnt(10)
	v_add_f32_e32 v96, 1.0, v96
	v_add_f32_e32 v97, 1.0, v97
	v_add_f32_e32 v98, 1.0, v98
	v_add_f32_e32 v99, 1.0, v99
	v_add_f32_e32 v100, 1.0, v100
	v_add_f32_e32 v101, 1.0, v101
	v_add_f32_e32 v102, 1.0, v102
	v_add_f32_e32 v103, 1.0, v103
	v_add_f32_e32 v104, 1.0, v104
	v_add_f32_e32 v105, 1.0, v105
	v_add_f32_e32 v106, 1.0, v106
	v_add_f32_e32 v107, 1.0, v107
	v_add_f32_e32 v108, 1.0, v108
	v_add_f32_e32 v109, 1.0, v109
	v_add_f32_e32 v110, 1.0, v110
	v_add_f32_e32 v111, 1.0, v111
	v_mul_f32_e32 v156, v16, v146
	v_mul_f32_e32 v157, v17, v146
	v_mul_f32_e32 v158, v18, v146
	v_mul_f32_e32 v159, v19, v146
	v_mul_f32_e32 v160, v20, v146
	v_mul_f32_e32 v161, v21, v146
	v_mul_f32_e32 v162, v22, v146
	v_mul_f32_e32 v163, v23, v146
	v_mul_f32_e32 v164, v24, v146
	v_mul_f32_e32 v165, v25, v146
	v_mul_f32_e32 v166, v26, v146
	v_mul_f32_e32 v167, v27, v146
	v_mul_f32_e32 v168, v28, v146
	v_mul_f32_e32 v169, v29, v146
	v_mul_f32_e32 v170, v30, v146
	v_mul_f32_e32 v171, v31, v146
	v_mul_f32_e32 v156, v64, v156
	v_mul_f32_e32 v157, v65, v157
	v_mul_f32_e32 v158, v66, v158
	v_mul_f32_e32 v159, v67, v159
	v_mul_f32_e32 v160, v68, v160
	v_mul_f32_e32 v161, v69, v161
	v_mul_f32_e32 v162, v70, v162
	v_mul_f32_e32 v163, v71, v163
	v_mul_f32_e32 v164, v72, v164
	v_mul_f32_e32 v165, v73, v165
	v_mul_f32_e32 v166, v74, v166
	v_mul_f32_e32 v167, v75, v167
	v_mul_f32_e32 v168, v76, v168
	v_mul_f32_e32 v169, v77, v169
	v_mul_f32_e32 v170, v78, v170
	v_mul_f32_e32 v171, v79, v171
	v_fma_f32 v156, v96, v156, v128
	v_fma_f32 v157, v97, v157, v129
	v_fma_f32 v158, v98, v158, v130
	v_fma_f32 v159, v99, v159, v131
	v_fma_f32 v160, v100, v160, v132
	v_fma_f32 v161, v101, v161, v133
	v_fma_f32 v162, v102, v162, v134
	v_fma_f32 v163, v103, v163, v135
	v_fma_f32 v164, v104, v164, v136
	v_fma_f32 v165, v105, v165, v137
	v_fma_f32 v166, v106, v166, v138
	v_fma_f32 v167, v107, v167, v139
	v_fma_f32 v168, v108, v168, v140
	v_fma_f32 v169, v109, v169, v141
	v_fma_f32 v170, v110, v170, v142
	v_fma_f32 v171, v111, v171, v143
	v_cvt_pk_bf16_f32 v148, v156, v157
	v_cvt_pk_bf16_f32 v149, v158, v159
	v_cvt_pk_bf16_f32 v150, v160, v161
	v_cvt_pk_bf16_f32 v151, v162, v163
	v_cvt_pk_bf16_f32 v152, v164, v165
	v_cvt_pk_bf16_f32 v153, v166, v167
	v_cvt_pk_bf16_f32 v154, v168, v169
	v_cvt_pk_bf16_f32 v155, v170, v171
	v_cndmask_b32_e32 v188, v150, v148, vcc
	v_cndmask_b32_e32 v189, v151, v149, vcc
	s_nop 1
	v_mov_b32_dpp v190, v188 quad_perm:[1,0,3,2] row_mask:0xf bank_mask:0xf
	v_mov_b32_dpp v191, v189 quad_perm:[1,0,3,2] row_mask:0xf bank_mask:0xf
	v_cndmask_b32_e32 v180, v148, v190, vcc
	v_cndmask_b32_e32 v181, v149, v191, vcc
	v_cndmask_b32_e32 v182, v190, v150, vcc
	v_cndmask_b32_e32 v183, v191, v151, vcc
	global_store_dwordx4 v177, v[180:183], s[12:13] sc1
	v_cndmask_b32_e32 v188, v154, v152, vcc
	v_cndmask_b32_e32 v189, v155, v153, vcc
	s_nop 1
	v_mov_b32_dpp v190, v188 quad_perm:[1,0,3,2] row_mask:0xf bank_mask:0xf
	v_mov_b32_dpp v191, v189 quad_perm:[1,0,3,2] row_mask:0xf bank_mask:0xf
	v_cndmask_b32_e32 v184, v152, v190, vcc
	v_cndmask_b32_e32 v185, v153, v191, vcc
	v_cndmask_b32_e32 v186, v190, v154, vcc
	v_cndmask_b32_e32 v187, v191, v155, vcc
	global_store_dwordx4 v177, v[184:187], s[12:13] offset:1024 sc1
	s_add_u32 s12, s12, 0x400000
	s_addc_u32 s13, s13, 0
	v_mul_f32_e32 v156, v32, v32
	v_mul_f32_e32 v157, v36, v36
	v_mul_f32_e32 v158, v40, v40
	v_mul_f32_e32 v159, v44, v44
	v_fmac_f32_e32 v156, v33, v33
	v_fmac_f32_e32 v157, v37, v37
	v_fmac_f32_e32 v158, v41, v41
	v_fmac_f32_e32 v159, v45, v45
	v_fmac_f32_e32 v156, v34, v34
	v_fmac_f32_e32 v157, v38, v38
	v_fmac_f32_e32 v158, v42, v42
	v_fmac_f32_e32 v159, v46, v46
	v_fmac_f32_e32 v156, v35, v35
	v_fmac_f32_e32 v157, v39, v39
	v_fmac_f32_e32 v158, v43, v43
	v_fmac_f32_e32 v159, v47, v47
	v_add_f32_e32 v156, v156, v157
	v_add_f32_e32 v158, v158, v159
	v_add_f32_e32 v144, v156, v158
	global_load_dwordx4 v[96:99], v172, s[16:17]
	global_load_dwordx4 v[100:103], v172, s[16:17] offset:1024
	global_load_dwordx4 v[104:107], v172, s[16:17] offset:2048
	global_load_dwordx4 v[108:111], v172, s[16:17] offset:3072
	global_load_dwordx4 v[128:131], v172, s[14:15]
	global_load_dwordx4 v[132:135], v172, s[14:15] offset:1024
	global_load_dwordx4 v[136:139], v172, s[14:15] offset:2048
	global_load_dwordx4 v[140:143], v172, s[14:15] offset:3072
	s_add_u32 s16, s16, 0x6000
	s_addc_u32 s17, s17, 0
	s_add_u32 s14, s14, 0x6000
	s_addc_u32 s15, s15, 0
	s_nop 1
	v_add_f32_dpp v144, v144, v144 quad_perm:[1,0,3,2] row_mask:0xf bank_mask:0xf bound_ctrl:1
	s_nop 1
	v_add_f32_dpp v144, v144, v144 quad_perm:[2,3,0,1] row_mask:0xf bank_mask:0xf bound_ctrl:1
	s_nop 1
	v_add_f32_dpp v144, v144, v144 row_half_mirror row_mask:0xf bank_mask:0xf bound_ctrl:1
	s_nop 1
	v_add_f32_dpp v144, v144, v144 row_mirror row_mask:0xf bank_mask:0xf bound_ctrl:1
	s_nop 1
	ds_bpermute_b32 v145, v174, v144
	s_waitcnt lgkmcnt(0)
	v_add_f32_e32 v144, v144, v145
	ds_bpermute_b32 v145, v175, v144
	s_waitcnt lgkmcnt(0)
	v_add_f32_e32 v144, v144, v145
	v_mov_b32_e32 v145, 0x358637bd
	v_fmac_f32_e32 v145, 0x3a800000, v144
	v_rsq_f32_e32 v146, v145
	s_nop 0
	s_waitcnt vmcnt(10)
	v_add_f32_e32 v80, 1.0, v80
	v_add_f32_e32 v81, 1.0, v81
	v_add_f32_e32 v82, 1.0, v82
	v_add_f32_e32 v83, 1.0, v83
	v_add_f32_e32 v84, 1.0, v84
	v_add_f32_e32 v85, 1.0, v85
	v_add_f32_e32 v86, 1.0, v86
	v_add_f32_e32 v87, 1.0, v87
	v_add_f32_e32 v88, 1.0, v88
	v_add_f32_e32 v89, 1.0, v89
	v_add_f32_e32 v90, 1.0, v90
	v_add_f32_e32 v91, 1.0, v91
	v_add_f32_e32 v92, 1.0, v92
	v_add_f32_e32 v93, 1.0, v93
	v_add_f32_e32 v94, 1.0, v94
	v_add_f32_e32 v95, 1.0, v95
	v_mul_f32_e32 v156, v32, v146
	v_mul_f32_e32 v157, v33, v146
	v_mul_f32_e32 v158, v34, v146
	v_mul_f32_e32 v159, v35, v146
	v_mul_f32_e32 v160, v36, v146
	v_mul_f32_e32 v161, v37, v146
	v_mul_f32_e32 v162, v38, v146
	v_mul_f32_e32 v163, v39, v146
	v_mul_f32_e32 v164, v40, v146
	v_mul_f32_e32 v165, v41, v146
	v_mul_f32_e32 v166, v42, v146
	v_mul_f32_e32 v167, v43, v146
	v_mul_f32_e32 v168, v44, v146
	v_mul_f32_e32 v169, v45, v146
	v_mul_f32_e32 v170, v46, v146
	v_mul_f32_e32 v171, v47, v146
	v_mul_f32_e32 v156, v64, v156
	v_mul_f32_e32 v157, v65, v157
	v_mul_f32_e32 v158, v66, v158
	v_mul_f32_e32 v159, v67, v159
	v_mul_f32_e32 v160, v68, v160
	v_mul_f32_e32 v161, v69, v161
	v_mul_f32_e32 v162, v70, v162
	v_mul_f32_e32 v163, v71, v163
	v_mul_f32_e32 v164, v72, v164
	v_mul_f32_e32 v165, v73, v165
	v_mul_f32_e32 v166, v74, v166
	v_mul_f32_e32 v167, v75, v167
	v_mul_f32_e32 v168, v76, v168
	v_mul_f32_e32 v169, v77, v169
	v_mul_f32_e32 v170, v78, v170
	v_mul_f32_e32 v171, v79, v171
	v_fma_f32 v156, v80, v156, v112
	v_fma_f32 v157, v81, v157, v113
	v_fma_f32 v158, v82, v158, v114
	v_fma_f32 v159, v83, v159, v115
	v_fma_f32 v160, v84, v160, v116
	v_fma_f32 v161, v85, v161, v117
	v_fma_f32 v162, v86, v162, v118
	v_fma_f32 v163, v87, v163, v119
	v_fma_f32 v164, v88, v164, v120
	v_fma_f32 v165, v89, v165, v121
	v_fma_f32 v166, v90, v166, v122
	v_fma_f32 v167, v91, v167, v123
	v_fma_f32 v168, v92, v168, v124
	v_fma_f32 v169, v93, v169, v125
	v_fma_f32 v170, v94, v170, v126
	v_fma_f32 v171, v95, v171, v127
	v_cvt_pk_bf16_f32 v148, v156, v157
	v_cvt_pk_bf16_f32 v149, v158, v159
	v_cvt_pk_bf16_f32 v150, v160, v161
	v_cvt_pk_bf16_f32 v151, v162, v163
	v_cvt_pk_bf16_f32 v152, v164, v165
	v_cvt_pk_bf16_f32 v153, v166, v167
	v_cvt_pk_bf16_f32 v154, v168, v169
	v_cvt_pk_bf16_f32 v155, v170, v171
	v_cndmask_b32_e32 v188, v150, v148, vcc
	v_cndmask_b32_e32 v189, v151, v149, vcc
	s_nop 1
	v_mov_b32_dpp v190, v188 quad_perm:[1,0,3,2] row_mask:0xf bank_mask:0xf
	v_mov_b32_dpp v191, v189 quad_perm:[1,0,3,2] row_mask:0xf bank_mask:0xf
	v_cndmask_b32_e32 v180, v148, v190, vcc
	v_cndmask_b32_e32 v181, v149, v191, vcc
	v_cndmask_b32_e32 v182, v190, v150, vcc
	v_cndmask_b32_e32 v183, v191, v151, vcc
	global_store_dwordx4 v177, v[180:183], s[12:13] sc1
	v_cndmask_b32_e32 v188, v154, v152, vcc
	v_cndmask_b32_e32 v189, v155, v153, vcc
	s_nop 1
	v_mov_b32_dpp v190, v188 quad_perm:[1,0,3,2] row_mask:0xf bank_mask:0xf
	v_mov_b32_dpp v191, v189 quad_perm:[1,0,3,2] row_mask:0xf bank_mask:0xf
	v_cndmask_b32_e32 v184, v152, v190, vcc
	v_cndmask_b32_e32 v185, v153, v191, vcc
	v_cndmask_b32_e32 v186, v190, v154, vcc
	v_cndmask_b32_e32 v187, v191, v155, vcc
	global_store_dwordx4 v177, v[184:187], s[12:13] offset:1024 sc1
	s_add_u32 s12, s12, 0x400000
	s_addc_u32 s13, s13, 0
	v_mul_f32_e32 v156, v48, v48
	v_mul_f32_e32 v157, v52, v52
	v_mul_f32_e32 v158, v56, v56
	v_mul_f32_e32 v159, v60, v60
	v_fmac_f32_e32 v156, v49, v49
	v_fmac_f32_e32 v157, v53, v53
	v_fmac_f32_e32 v158, v57, v57
	v_fmac_f32_e32 v159, v61, v61
	v_fmac_f32_e32 v156, v50, v50
	v_fmac_f32_e32 v157, v54, v54
	v_fmac_f32_e32 v158, v58, v58
	v_fmac_f32_e32 v159, v62, v62
	v_fmac_f32_e32 v156, v51, v51
	v_fmac_f32_e32 v157, v55, v55
	v_fmac_f32_e32 v158, v59, v59
	v_fmac_f32_e32 v159, v63, v63
	v_add_f32_e32 v156, v156, v157
	v_add_f32_e32 v158, v158, v159
	v_add_f32_e32 v144, v156, v158
	s_nop 1
	v_add_f32_dpp v144, v144, v144 quad_perm:[1,0,3,2] row_mask:0xf bank_mask:0xf bound_ctrl:1
	s_nop 1
	v_add_f32_dpp v144, v144, v144 quad_perm:[2,3,0,1] row_mask:0xf bank_mask:0xf bound_ctrl:1
	s_nop 1
	v_add_f32_dpp v144, v144, v144 row_half_mirror row_mask:0xf bank_mask:0xf bound_ctrl:1
	s_nop 1
	v_add_f32_dpp v144, v144, v144 row_mirror row_mask:0xf bank_mask:0xf bound_ctrl:1
	s_nop 1
	ds_bpermute_b32 v145, v174, v144
	s_waitcnt lgkmcnt(0)
	v_add_f32_e32 v144, v144, v145
	ds_bpermute_b32 v145, v175, v144
	s_waitcnt lgkmcnt(0)
	v_add_f32_e32 v144, v144, v145
	v_mov_b32_e32 v145, 0x358637bd
	v_fmac_f32_e32 v145, 0x3a800000, v144
	v_rsq_f32_e32 v146, v145
	s_nop 0
	s_waitcnt vmcnt(2)
	v_add_f32_e32 v96, 1.0, v96
	v_add_f32_e32 v97, 1.0, v97
	v_add_f32_e32 v98, 1.0, v98
	v_add_f32_e32 v99, 1.0, v99
	v_add_f32_e32 v100, 1.0, v100
	v_add_f32_e32 v101, 1.0, v101
	v_add_f32_e32 v102, 1.0, v102
	v_add_f32_e32 v103, 1.0, v103
	v_add_f32_e32 v104, 1.0, v104
	v_add_f32_e32 v105, 1.0, v105
	v_add_f32_e32 v106, 1.0, v106
	v_add_f32_e32 v107, 1.0, v107
	v_add_f32_e32 v108, 1.0, v108
	v_add_f32_e32 v109, 1.0, v109
	v_add_f32_e32 v110, 1.0, v110
	v_add_f32_e32 v111, 1.0, v111
	v_mul_f32_e32 v156, v48, v146
	v_mul_f32_e32 v157, v49, v146
	v_mul_f32_e32 v158, v50, v146
	v_mul_f32_e32 v159, v51, v146
	v_mul_f32_e32 v160, v52, v146
	v_mul_f32_e32 v161, v53, v146
	v_mul_f32_e32 v162, v54, v146
	v_mul_f32_e32 v163, v55, v146
	v_mul_f32_e32 v164, v56, v146
	v_mul_f32_e32 v165, v57, v146
	v_mul_f32_e32 v166, v58, v146
	v_mul_f32_e32 v167, v59, v146
	v_mul_f32_e32 v168, v60, v146
	v_mul_f32_e32 v169, v61, v146
	v_mul_f32_e32 v170, v62, v146
	v_mul_f32_e32 v171, v63, v146
	v_mul_f32_e32 v156, v64, v156
	v_mul_f32_e32 v157, v65, v157
	v_mul_f32_e32 v158, v66, v158
	v_mul_f32_e32 v159, v67, v159
	v_mul_f32_e32 v160, v68, v160
	v_mul_f32_e32 v161, v69, v161
	v_mul_f32_e32 v162, v70, v162
	v_mul_f32_e32 v163, v71, v163
	v_mul_f32_e32 v164, v72, v164
	v_mul_f32_e32 v165, v73, v165
	v_mul_f32_e32 v166, v74, v166
	v_mul_f32_e32 v167, v75, v167
	v_mul_f32_e32 v168, v76, v168
	v_mul_f32_e32 v169, v77, v169
	v_mul_f32_e32 v170, v78, v170
	v_mul_f32_e32 v171, v79, v171
	v_fma_f32 v156, v96, v156, v128
	v_fma_f32 v157, v97, v157, v129
	v_fma_f32 v158, v98, v158, v130
	v_fma_f32 v159, v99, v159, v131
	v_fma_f32 v160, v100, v160, v132
	v_fma_f32 v161, v101, v161, v133
	v_fma_f32 v162, v102, v162, v134
	v_fma_f32 v163, v103, v163, v135
	v_fma_f32 v164, v104, v164, v136
	v_fma_f32 v165, v105, v165, v137
	v_fma_f32 v166, v106, v166, v138
	v_fma_f32 v167, v107, v167, v139
	v_fma_f32 v168, v108, v168, v140
	v_fma_f32 v169, v109, v169, v141
	v_fma_f32 v170, v110, v170, v142
	v_fma_f32 v171, v111, v171, v143
	v_cvt_pk_bf16_f32 v148, v156, v157
	v_cvt_pk_bf16_f32 v149, v158, v159
	v_cvt_pk_bf16_f32 v150, v160, v161
	v_cvt_pk_bf16_f32 v151, v162, v163
	v_cvt_pk_bf16_f32 v152, v164, v165
	v_cvt_pk_bf16_f32 v153, v166, v167
	v_cvt_pk_bf16_f32 v154, v168, v169
	v_cvt_pk_bf16_f32 v155, v170, v171
	v_cndmask_b32_e32 v188, v150, v148, vcc
	v_cndmask_b32_e32 v189, v151, v149, vcc
	s_nop 1
	v_mov_b32_dpp v190, v188 quad_perm:[1,0,3,2] row_mask:0xf bank_mask:0xf
	v_mov_b32_dpp v191, v189 quad_perm:[1,0,3,2] row_mask:0xf bank_mask:0xf
	v_cndmask_b32_e32 v180, v148, v190, vcc
	v_cndmask_b32_e32 v181, v149, v191, vcc
	v_cndmask_b32_e32 v182, v190, v150, vcc
	v_cndmask_b32_e32 v183, v191, v151, vcc
	global_store_dwordx4 v177, v[180:183], s[12:13] sc1
	v_cndmask_b32_e32 v188, v154, v152, vcc
	v_cndmask_b32_e32 v189, v155, v153, vcc
	s_nop 1
	v_mov_b32_dpp v190, v188 quad_perm:[1,0,3,2] row_mask:0xf bank_mask:0xf
	v_mov_b32_dpp v191, v189 quad_perm:[1,0,3,2] row_mask:0xf bank_mask:0xf
	v_cndmask_b32_e32 v184, v152, v190, vcc
	v_cndmask_b32_e32 v185, v153, v191, vcc
	v_cndmask_b32_e32 v186, v190, v154, vcc
	v_cndmask_b32_e32 v187, v191, v155, vcc
	global_store_dwordx4 v177, v[184:187], s[12:13] offset:1024 sc1
	s_add_u32 s12, s12, 0x400000
	s_addc_u32 s13, s13, 0
	s_branch .LBB0_177
	s_nop 0
	s_nop 0
	s_nop 0
	s_nop 0
	s_nop 0
	s_nop 0
	s_nop 0
	s_nop 0
	s_nop 0
	s_nop 0
	s_nop 0
